# MoBA tile loop: t+2 K/V prefetch issued before the tile barrier (after lgkmcnt(0) retires the staging ds_writes) instead of after the K-fragment reads
# speedup vs baseline: 1.0093x; 1.0038x over previous
; #define ALAS __attribute__((address_space(3)))
; __device__ __forceinline__ int kperm(int i) { return (i & 19) | ((i & 4) << 1) | ((i & 8) >> 1); }
; template <int OFF> __device__ __forceinline__ void ldsr(bf16x8& d, unsigned a) { asm volatile("ds_read_b128 %0, %1 offset:%c2" : "=v"(d) : "v"(a), "i"(OFF) : "memory"); }
; __device__ __forceinline__ void qk_tile(f32x16& s0, f32x16& s1, float ci, const ALAS unsigned char* Kb, const bf16x8 (&qf)[4], int r32, int hi) {
;     const unsigned p0 = (unsigned)(uintptr_t)(Kb + kperm(r32) * ROWB + hi * 16);
;     bf16x8 a[8];
;     ldsr<0>(a[0], p0); ldsr<32 * ROWB>(a[1], p0); ldsr<32>(a[2], p0); ldsr<32 * ROWB + 32>(a[3], p0);
;     ldsr<64>(a[4], p0); ldsr<32 * ROWB + 64>(a[5], p0); ldsr<96>(a[6], p0); ldsr<32 * ROWB + 96>(a[7], p0);
; __device__ __forceinline__ void moba_unit(int b, int h, int j, const bf16_t* Q, const bf16_t* K, const bf16_t* VT, bf16_t* O, const float* biasd, const float* kmean, ALAS unsigned char* lds) {
;     ...
;         ALAS unsigned char* buf = lds + (t & 1) * 18432;
;         *(ALAS u32x4*)(buf + kl) = kr; *(ALAS u32x4*)(buf + vl) = vr;
;         __syncthreads();
;         if (t + 1 < NT) { const int t1 = t + 1; const int kb1 = (t1 < 4) ? (256 * j + 64 * t1) : (64 * (t1 - 4));
;             kr = *(const u32x4*)(kg + (size_t)kb1 * 1024); vr = *(const u32x4*)(vg + kb1); }
.Lmb_wgob:
	ds_write_b128 v32, v[160:163]
	ds_write_b128 v32, v[164:167] offset:9216
	s_add_i32 s18, s96, s15
	s_add_i32 s0, s16, 6
	s_cmp_lt_i32 s0, s14
	s_waitcnt lgkmcnt(0)
	s_cbranch_scc0 .Lmb_noldb
	s_add_i32 s0, s18, 0x180
	s_add_i32 s1, s15, 0x80
	s_cmp_lt_u32 s8, 2
	s_cselect_b32 s0, s0, s1
	s_ashr_i32 s1, s0, 31
	s_lshl_b64 s[6:7], s[0:1], 11
	v_lshl_add_u64 v[32:33], v[94:95], 0, s[6:7]
	v_lshl_add_u64 v[34:35], s[0:1], 1, v[96:97]
	global_load_dwordx4 v[160:163], v[32:33], off
	global_load_dwordx4 v[164:167], v[34:35], off
.Lmb_noldb:
	s_barrier
	v_add3_u32 v216, s17, v105, v144
	ds_read_b128 v[108:111], v216 offset:0
	ds_read_b128 v[112:115], v216 offset:4608
	ds_read_b128 v[116:119], v216 offset:32
	ds_read_b128 v[120:123], v216 offset:4640
	ds_read_b128 v[124:127], v216 offset:64
	ds_read_b128 v[128:131], v216 offset:4672
	ds_read_b128 v[132:135], v216 offset:96
	ds_read_b128 v[136:139], v216 offset:4704

; #define ALAS __attribute__((address_space(3)))
; __device__ __forceinline__ void moba_unit(int b, int h, int j, const bf16_t* Q, const bf16_t* K, const bf16_t* VT, bf16_t* O, const float* biasd, const float* kmean, ALAS unsigned char* lds) {
;     ...
;         ALAS unsigned char* buf = lds + (t & 1) * 18432;
;         *(ALAS u32x4*)(buf + kl) = kr; *(ALAS u32x4*)(buf + vl) = vr;
;         __syncthreads();
;         if (t + 1 < NT) { const int t1 = t + 1; const int kb1 = (t1 < 4) ? (256 * j + 64 * t1) : (64 * (t1 - 4));
;             kr = *(const u32x4*)(kg + (size_t)kb1 * 1024); vr = *(const u32x4*)(vg + kb1); }
.Lmb_wgo:
	ds_write_b128 v32, v[80:83]
	ds_write_b128 v32, v[84:87] offset:9216
	s_add_i32 s18, s96, s15
	s_add_i32 s0, s16, 6
	s_cmp_lt_i32 s0, s14
	s_waitcnt lgkmcnt(0)
	s_cbranch_scc0 .Lmb_nold
	s_add_i32 s0, s18, 0x180
	s_add_i32 s1, s15, 0x80
	s_cmp_lt_u32 s8, 2
	s_cselect_b32 s0, s0, s1
	s_ashr_i32 s1, s0, 31
	s_lshl_b64 s[6:7], s[0:1], 11
	v_lshl_add_u64 v[32:33], v[94:95], 0, s[6:7]
	v_lshl_add_u64 v[34:35], s[0:1], 1, v[96:97]
	global_load_dwordx4 v[80:83], v[32:33], off
	global_load_dwordx4 v[84:87], v[34:35], off
